# diff-attention tile loop: LDS-DMA pieces interleaved into the QK MFMA chain (saddr form, no VALU) instead of a burst at the tile head; plus MLA long-unit loop rewrite
# speedup vs baseline: 1.0104x; 1.0067x over previous
; template <bool DIFF, bool NOMAX>
; DI void unit(LAS unsigned char* lds, const Tensors& Tn, int b, int hd, int qb) {
;     ...
;     for (int j = jbeg; j < ntiles; ++j) {
;         const int sbn = (sb + NSTG - 1 >= NSTG) ? sb - 1 : sb + NSTG - 1;
;         if (j + NSTG - 1 < ntiles) ATT_ISSUE(j + NSTG - 1, sbn);
;         if (j >= jst && j < need) {
.LBB0_784:
	s_add_i32 s29, s4, 1
	s_add_i32 s28, s82, 1
	s_add_i32 s98, s4, -1
	s_cmp_gt_i32 s4, 0
	s_cselect_b32 s98, s98, s29
	s_mul_i32 s98, s98, 0x11400
	s_cmp_ge_i32 s28, s86
	s_cselect_b64 s[74:75], -1, 0
	s_and_b64 vcc, exec, s[74:75]
	s_cbranch_vccnz .LBB0_795
	s_cmp_lt_i32 s82, s25
	s_cselect_b64 s[76:77], -1, 0
	s_cmp_gt_i32 s82, s24
	s_cselect_b64 s[88:89], -1, 0
	s_or_b64 s[76:77], s[76:77], s[88:89]
	s_and_b64 vcc, exec, s[76:77]
	s_cbranch_vccz .LBB0_795
	s_add_i32 s5, s4, -1
	s_cmp_gt_i32 s4, 0
	s_cselect_b32 s5, s5, s29
	s_mul_i32 s5, s5, 0x11400
	s_andn2_b64 vcc, exec, s[6:7]
	s_add_i32 s5, s5, 0
	s_cbranch_vccz .LBB0_811
	s_andn2_b64 vcc, exec, s[56:57]
	s_cbranch_vccz .LBB0_812

; DI f32x16 mfma32(bf16x8 a, bf16x8 b, f32x16 c) { return __builtin_amdgcn_mfma_f32_32x32x16_bf16(a, b, c, 0, 0, 0); }
; #define SGB(mask, n) __builtin_amdgcn_sched_group_barrier(mask, n, 0)
; #define LDV(i_, hf_) do { VTR(vlo[(i_) % DV], (16 * (2 * (hf_) + ((i_) & 1))) * VSTR + 64 * ((i_) >> 1)); VTR(vhi[(i_) % DV], (16 * (2 * (hf_) + ((i_) & 1)) + 8) * VSTR + 64 * ((i_) >> 1)); } while (0)
; template <bool DIFF, bool NOMAX>
; DI void unit(LAS unsigned char* lds, const Tensors& Tn, int b, int hd, int qb) {
;     ...
; #pragma unroll
;                 for (int ks = 0; ks < NKS; ++ks) {
;                     sc = mfma32(kf[ks % DK], qf[ks], sc);
;                     if (ks + DK < NKS) kf[ks % DK] = LDK(hf, ks + DK);
;                 }
; #pragma unroll
;                 for (int ks = 0; ks < NKS; ++ks) { SGB(0x8, 1); if (ks + DK < NKS) SGB(0x100, 1); }
;                 __builtin_amdgcn_sched_barrier(0);
; #pragma unroll
;                 for (int i = 0; i < DV; ++i) LDV(i, hf);
;                 if (DIFF && !offd) {
;                     const float qk = (float)(q0 + r - 64 * j - 4 * h - 32 * hf);
;                     float tq[4] = {qk, qk - 8.f, qk - 16.f, qk - 24.f};
; #pragma unroll
;                     for (int g = 0; g < 4; ++g) asm volatile("" : "+v"(tq[g]));
; #pragma unroll
;                     for (int e = 0; e < 16; ++e) sc[e] = __builtin_fmaf(-sl2, __builtin_fabsf(tq[e >> 2] - (float)(e & 3)), sc[e]);
;                 }
.LBB0_800:
	s_waitcnt lgkmcnt(0)
	s_nop 0
	v_mfma_f32_32x32x16_bf16 v[132:147], v[192:195], v[148:151], v[132:147]
	s_and_b64 vcc, exec, s[74:75]
	s_cbranch_vccnz .Ldf_skip0
	s_andn2_b64 vcc, exec, s[6:7]
	s_cbranch_vccnz .Ldf_skip0
	s_add_i32 m0, s98, s50
	s_nop 0
	global_load_lds_dwordx4 v204, s[72:73]
.Ldf_skip0:
	ds_read_b128 v[192:195], v250 offset:128
	v_mfma_f32_32x32x16_bf16 v[132:147], v[188:191], v[152:155], v[132:147]
	s_and_b64 vcc, exec, s[74:75]
	s_cbranch_vccnz .Ldf_skip1
	s_andn2_b64 vcc, exec, s[56:57]
	s_cbranch_vccnz .Ldf_skip1
	s_add_i32 m0, s98, s26
	s_nop 0
	global_load_lds_dwordx4 v206, s[72:73]
.Ldf_skip1:
	ds_read_b128 v[188:191], v250 offset:160
	v_mfma_f32_32x32x16_bf16 v[132:147], v[184:187], v[156:159], v[132:147]
	s_and_b64 vcc, exec, s[74:75]
	s_cbranch_vccnz .Ldf_skip2
	s_andn2_b64 vcc, exec, s[58:59]
	s_cbranch_vccnz .Ldf_skip2
	s_add_i32 m0, s98, s27
	s_nop 0
	global_load_lds_dwordx4 v208, s[72:73]
.Ldf_skip2:
	ds_read_b128 v[184:187], v250 offset:192
	v_mfma_f32_32x32x16_bf16 v[132:147], v[180:183], v[160:163], v[132:147]
	s_and_b64 vcc, exec, s[74:75]
	s_cbranch_vccnz .Ldf_skip3
	s_andn2_b64 vcc, exec, s[60:61]
	s_cbranch_vccnz .Ldf_skip3
	s_add_i32 m0, s98, s51
	s_nop 0
	global_load_lds_dwordx4 v210, s[72:73]
.Ldf_skip3:
	ds_read_b128 v[180:183], v250 offset:224
	s_waitcnt lgkmcnt(0)
	v_mfma_f32_32x32x16_bf16 v[132:147], v[192:195], v[164:167], v[132:147]
	s_and_b64 vcc, exec, s[74:75]
	s_cbranch_vccnz .Ldf_skip4
	s_andn2_b64 vcc, exec, s[62:63]
	s_cbranch_vccnz .Ldf_skip4
	s_add_i32 m0, s98, s46
	s_nop 0
	global_load_lds_dwordx4 v212, s[72:73]
.Ldf_skip4:
	v_mfma_f32_32x32x16_bf16 v[132:147], v[188:191], v[168:171], v[132:147]
	s_and_b64 vcc, exec, s[74:75]
	s_cbranch_vccnz .Ldf_skip5
	s_andn2_b64 vcc, exec, s[64:65]
	s_cbranch_vccnz .Ldf_skip5
	s_add_i32 m0, s98, s47
	s_nop 0
	global_load_lds_dwordx4 v214, s[72:73]
.Ldf_skip5:
	v_mfma_f32_32x32x16_bf16 v[132:147], v[184:187], v[172:175], v[132:147]
	s_and_b64 vcc, exec, s[74:75]
	s_cbranch_vccnz .Ldf_skip6
	s_andn2_b64 vcc, exec, s[66:67]
	s_cbranch_vccnz .Ldf_skip6
	s_add_i32 m0, s98, s79
	s_nop 0
	global_load_lds_dwordx4 v216, s[72:73]
.Ldf_skip6:
	v_add_u32_e32 v184, s83, v245
	v_add3_u32 v249, v184, v246, s84
	v_mfma_f32_32x32x16_bf16 v[132:147], v[180:183], v[176:179], v[132:147]
	s_and_b64 vcc, exec, s[74:75]
	s_cbranch_vccnz .Ldf_skip7
	s_andn2_b64 vcc, exec, s[68:69]
	s_cbranch_vccnz .Ldf_skip7
	s_add_i32 m0, s98, s80
	s_nop 0
	global_load_lds_dwordx4 v218, s[72:73]
.Ldf_skip7:
	s_and_b64 vcc, exec, s[74:75]
	s_cbranch_vccnz .Ldf_skip8
	s_andn2_b64 vcc, exec, s[70:71]
	s_cbranch_vccnz .Ldf_skip8
	s_add_i32 m0, s98, s81
	s_nop 0
	global_load_lds_dwordx4 v220, s[72:73]
.Ldf_skip8:
	ds_read_b64_tr_b16 v[184:185], v249 offset:0
	ds_read_b64_tr_b16 v[186:187], v249 offset:4608
	ds_read_b64_tr_b16 v[180:181], v249 offset:9216
	v_cndmask_b32_e64 v182, 0, 1, s[76:77]
	v_cmp_ne_u32_e64 s[4:5], 1, v182
	ds_read_b64_tr_b16 v[182:183], v249 offset:13824
	s_andn2_b64 vcc, exec, s[76:77]
	s_cbranch_vccnz .LBB0_802
	v_add_u32_e32 v188, 32, v248
	v_cvt_f32_i32_e32 v188, v188
	v_mov_b32_e32 v201, v200
	v_add_f32_e32 v190, 0xc1000000, v188
	v_add_f32_e32 v192, 0xc1800000, v188
	v_add_f32_e32 v194, 0xc1c00000, v188
	s_nop 0
	v_add_f32_e32 v189, -1.0, v188
	v_add_f32_e32 v191, -1.0, v190
	v_add_f32_e32 v193, -1.0, v192
	v_add_f32_e32 v195, -1.0, v194
	v_pk_add_f32 v[222:223], v[188:189], s[54:55] op_sel_hi:[0,1]
	v_pk_add_f32 v[224:225], v[190:191], s[54:55] op_sel_hi:[0,1]
	v_pk_add_f32 v[226:227], v[192:193], s[54:55] op_sel_hi:[0,1]
	v_pk_add_f32 v[228:229], v[194:195], s[54:55] op_sel_hi:[0,1]
	v_and_b32_e32 v229, 0x7fffffff, v229
	v_and_b32_e32 v228, 0x7fffffff, v228
	v_and_b32_e32 v227, 0x7fffffff, v227
	v_and_b32_e32 v226, 0x7fffffff, v226
	v_and_b32_e32 v225, 0x7fffffff, v225
	v_and_b32_e32 v224, 0x7fffffff, v224
	v_and_b32_e32 v223, 0x7fffffff, v223
	v_and_b32_e32 v222, 0x7fffffff, v222
	v_and_b32_e32 v194, 0x7fffffff, v194
	v_and_b32_e32 v195, 0x7fffffff, v195
	v_and_b32_e32 v192, 0x7fffffff, v192
	v_and_b32_e32 v193, 0x7fffffff, v193
	v_and_b32_e32 v190, 0x7fffffff, v190
	v_and_b32_e32 v191, 0x7fffffff, v191
	v_and_b32_e32 v188, 0x7fffffff, v188
	v_and_b32_e32 v189, 0x7fffffff, v189
	v_pk_fma_f32 v[134:135], v[200:201], v[222:223], v[134:135]
	v_pk_fma_f32 v[138:139], v[200:201], v[224:225], v[138:139]
	v_pk_fma_f32 v[142:143], v[200:201], v[226:227], v[142:143]
	v_pk_fma_f32 v[146:147], v[200:201], v[228:229], v[146:147]
	v_pk_fma_f32 v[132:133], v[202:203], v[188:189], v[132:133]
	v_pk_fma_f32 v[136:137], v[200:201], v[190:191], v[136:137]
	v_pk_fma_f32 v[140:141], v[200:201], v[192:193], v[140:141]
	v_pk_fma_f32 v[144:145], v[200:201], v[194:195], v[144:145]

; DI float fast_exp2(float x) { return __builtin_amdgcn_exp2f(x); }
; template <bool DIFF, bool NOMAX>
; DI void unit(LAS unsigned char* lds, const Tensors& Tn, int b, int hd, int qb) {
;     ...
; #pragma unroll
;                 for (int ks = 0; ks < NKS; ++ks) {
;                     sc = mfma32(kf[ks % DK], qf[ks], sc);
;                     if (ks + DK < NKS) kf[ks % DK] = LDK(hf, ks + DK);
;                 }
; #pragma unroll
;                 for (int ks = 0; ks < NKS; ++ks) { SGB(0x8, 1); if (ks + DK < NKS) SGB(0x100, 1); }
;                 __builtin_amdgcn_sched_barrier(0);
; #pragma unroll
;                 for (int i = 0; i < DV; ++i) LDV(i, hf);
;                 if (DIFF && !offd) {
;                     const float qk = (float)(q0 + r - 64 * j - 4 * h - 32 * hf);
;                     float tq[4] = {qk, qk - 8.f, qk - 16.f, qk - 24.f};
; #pragma unroll
;                     for (int g = 0; g < 4; ++g) asm volatile("" : "+v"(tq[g]));
; #pragma unroll
;                     for (int e = 0; e < 16; ++e) sc[e] = __builtin_fmaf(-sl2, __builtin_fabsf(tq[e >> 2] - (float)(e & 3)), sc[e]);
;                 }
;                 float mx = sc[0];
;                 if (!NOMAX) {
; #pragma unroll
;                 for (int e = 1; e < 16; ++e) mx = __builtin_fmaxf(mx, sc[e]);
;                 { auto rr = __builtin_amdgcn_permlane32_swap(__builtin_bit_cast(unsigned, mx), __builtin_bit_cast(unsigned, mx), false, false);
;                   mx = __builtin_fmaxf(__builtin_bit_cast(float, rr[0]), __builtin_bit_cast(float, rr[1])); }
;                 }
;                 const bool first = (j == jst) && (hf == 0);
;                 if (!NOMAX && (first || __any(mx > 8.0f))) {
;                     const float mn = first ? mx : __builtin_fmaxf(mx, 0.f), al = first ? 1.0f : fast_exp2(-mn);
; #pragma unroll
;                     for (int dt = 0; dt < NDT; ++dt) o[dt] = o[dt] * al;
;                     lrow *= al; mrow += mn;
; #pragma unroll
;                     for (int e = 0; e < 16; ++e) sc[e] -= mn;
;                 }
;                 f32x2_t ps2 = {0.f, 0.f};
; #pragma unroll
;                 for (int e = 0; e < 16; e += 2) { sc[e] = fast_exp2(sc[e]); sc[e + 1] = fast_exp2(sc[e + 1]); ps2 += (f32x2_t){sc[e], sc[e + 1]}; }
;                 lrow += ps2.x + ps2.y;
;                 bf16x8 pb[2]; pb[0] = pack8(sc, 0); pb[1] = pack8(sc, 1);
.LBB0_1389:
	s_mul_i32 s80, s51, 0xb400
	s_add_i32 s80, s80, 0
	v_add3_u32 v0, s80, v170, v144
	s_add_i32 s99, s84, 2
	s_cmp_lt_u32 s99, s29
	s_cselect_b32 s99, 1, 0
	s_cmp_gt_i32 s51, 0
	s_cselect_b32 s98, -1, 2
	s_add_i32 s98, s98, s51
	s_mul_i32 s98, s98, 0xb400
	v_mov_b32_e32 v196, 0
	ds_read_b128 v[2:5], v0
	ds_read_b128 v[6:9], v0 offset:32
	ds_read_b128 v[10:13], v0 offset:64
	ds_read_b128 v[174:177], v0 offset:96
	ds_read_b128 v[178:181], v0 offset:128
	ds_read_b128 v[182:185], v0 offset:160
	v_add_u32_e32 v14, s80, v145
	v_add3_u32 v173, v14, v171, s1
	s_waitcnt lgkmcnt(5)
	v_mfma_f32_32x32x16_bf16 v[80:95], v[2:5], v[96:99], 0
	ds_read_b128 v[2:5], v0 offset:192
	s_waitcnt lgkmcnt(5)
	v_mfma_f32_32x32x16_bf16 v[80:95], v[6:9], v[100:103], v[80:95]
	ds_read_b128 v[6:9], v0 offset:224
	s_waitcnt lgkmcnt(5)
	v_mfma_f32_32x32x16_bf16 v[80:95], v[10:13], v[104:107], v[80:95]
	ds_read_b128 v[10:13], v0 offset:256
	s_waitcnt lgkmcnt(5)
	v_mfma_f32_32x32x16_bf16 v[80:95], v[174:177], v[108:111], v[80:95]
	ds_read_b128 v[174:177], v0 offset:288
	s_cmp_lg_u32 s99, 0
	s_cbranch_scc0 .Lpc_skip0_i1
	s_and_b64 vcc, exec, s[4:5]
	s_cbranch_vccnz .Lpc_skip0_i1
	v_lshl_add_u64 v[244:245], s[36:37], 0, v[146:147]
	v_lshl_add_u64 v[246:247], s[36:37], 0, v[158:159]
	v_cndmask_b32_e64 v245, v247, v245, s[14:15]
	v_cndmask_b32_e64 v244, v246, v244, s[14:15]
	s_add_i32 m0, s98, s41
	s_nop 0
	global_load_lds_dwordx4 v[244:245], off
.Lpc_skip0_i1:
	s_waitcnt lgkmcnt(5)
	v_mfma_f32_32x32x16_bf16 v[80:95], v[178:181], v[112:115], v[80:95]
	ds_read_b128 v[178:181], v0 offset:320
	s_waitcnt lgkmcnt(5)
	v_mfma_f32_32x32x16_bf16 v[80:95], v[182:185], v[116:119], v[80:95]
	ds_read_b128 v[182:185], v0 offset:352
	s_waitcnt lgkmcnt(5)
	v_mfma_f32_32x32x16_bf16 v[80:95], v[2:5], v[120:123], v[80:95]
	ds_read_b128 v[2:5], v0 offset:12800
	s_waitcnt lgkmcnt(5)
	v_mfma_f32_32x32x16_bf16 v[80:95], v[6:9], v[124:127], v[80:95]
	ds_read_b128 v[6:9], v0 offset:12832
	s_waitcnt lgkmcnt(5)
	v_mfma_f32_32x32x16_bf16 v[80:95], v[10:13], v[128:131], v[80:95]
	ds_read_b128 v[10:13], v0 offset:12864
	s_waitcnt lgkmcnt(5)
	v_mfma_f32_32x32x16_bf16 v[80:95], v[174:177], v[132:135], v[80:95]
	ds_read_b128 v[174:177], v0 offset:12896
	s_waitcnt lgkmcnt(5)
	v_mfma_f32_32x32x16_bf16 v[80:95], v[178:181], v[136:139], v[80:95]
	ds_read_b128 v[178:181], v0 offset:12928
	s_cmp_lg_u32 s99, 0
	s_cbranch_scc0 .Lpc_skip1_i1
	s_and_b64 vcc, exec, s[6:7]
	s_cbranch_vccnz .Lpc_skip1_i1
	v_lshl_add_u64 v[244:245], s[36:37], 0, v[148:149]
	v_lshl_add_u64 v[246:247], s[36:37], 0, v[160:161]
	v_cndmask_b32_e64 v245, v247, v245, s[16:17]
	v_cndmask_b32_e64 v244, v246, v244, s[16:17]
	s_add_i32 m0, s98, s56
	s_nop 0
	global_load_lds_dwordx4 v[244:245], off
.Lpc_skip1_i1:
	s_waitcnt lgkmcnt(5)
	v_mfma_f32_32x32x16_bf16 v[80:95], v[182:185], v[140:143], v[80:95]
	ds_read_b128 v[182:185], v0 offset:12960
	s_waitcnt lgkmcnt(5)
	v_mfma_f32_32x32x16_bf16 v[226:241], v[2:5], v[96:99], 0
	ds_read_b128 v[2:5], v0 offset:12992
	s_waitcnt lgkmcnt(5)
	v_mfma_f32_32x32x16_bf16 v[226:241], v[6:9], v[100:103], v[226:241]
	ds_read_b128 v[6:9], v0 offset:13024
	s_waitcnt lgkmcnt(5)
	v_mfma_f32_32x32x16_bf16 v[226:241], v[10:13], v[104:107], v[226:241]
	ds_read_b128 v[10:13], v0 offset:13056
	s_waitcnt lgkmcnt(5)
	v_mfma_f32_32x32x16_bf16 v[226:241], v[174:177], v[108:111], v[226:241]
	ds_read_b128 v[174:177], v0 offset:13088
	v_exp_f32_e32 v80, v80
	v_exp_f32_e32 v81, v81
	v_add_f32_e32 v172, v172, v80
	v_add_f32_e32 v196, v196, v81
	s_waitcnt lgkmcnt(5)
	v_mfma_f32_32x32x16_bf16 v[226:241], v[178:181], v[112:115], v[226:241]
	ds_read_b128 v[178:181], v0 offset:13120
	v_cvt_pk_bf16_f32 v80, v80, v81
	v_exp_f32_e32 v82, v82
	v_exp_f32_e32 v83, v83
	v_add_f32_e32 v172, v172, v82
	s_waitcnt lgkmcnt(5)
	v_mfma_f32_32x32x16_bf16 v[226:241], v[182:185], v[116:119], v[226:241]
	ds_read_b128 v[182:185], v0 offset:13152
	v_add_f32_e32 v196, v196, v83
	v_cvt_pk_bf16_f32 v81, v82, v83
	v_exp_f32_e32 v84, v84
	v_exp_f32_e32 v85, v85
	s_cmp_lg_u32 s99, 0
	s_cbranch_scc0 .Lpc_skip2_i1
	s_and_b64 vcc, exec, s[8:9]
	s_cbranch_vccnz .Lpc_skip2_i1
	v_lshl_add_u64 v[244:245], s[36:37], 0, v[150:151]
	v_lshl_add_u64 v[246:247], s[36:37], 0, v[162:163]
	v_cndmask_b32_e64 v245, v247, v245, s[18:19]
	v_cndmask_b32_e64 v244, v246, v244, s[18:19]
	s_add_i32 m0, s98, s57
	s_nop 0
	global_load_lds_dwordx4 v[244:245], off
; DI float fast_exp2(float x) { return __builtin_amdgcn_exp2f(x); }
; DI f32x16 mfma32(bf16x8 a, bf16x8 b, f32x16 c) { return __builtin_amdgcn_mfma_f32_32x32x16_bf16(a, b, c, 0, 0, 0); }
; #define LDV(i_, hf_) do { VTR(vlo[(i_) % DV], (16 * (2 * (hf_) + ((i_) & 1))) * VSTR + 64 * ((i_) >> 1)); VTR(vhi[(i_) % DV], (16 * (2 * (hf_) + ((i_) & 1)) + 8) * VSTR + 64 * ((i_) >> 1)); } while (0)
; #define VWAIT(n_, a_, b_) asm volatile("s_waitcnt lgkmcnt(%c2)" : "+v"(a_), "+v"(b_) : "i"(n_) : "memory")
; template <bool DIFF, bool NOMAX>
; DI void unit(LAS unsigned char* lds, const Tensors& Tn, int b, int hd, int qb) {
;     ...
;                 f32x2_t ps2 = {0.f, 0.f};
; #pragma unroll
;                 for (int e = 0; e < 16; e += 2) { sc[e] = fast_exp2(sc[e]); sc[e + 1] = fast_exp2(sc[e + 1]); ps2 += (f32x2_t){sc[e], sc[e + 1]}; }
;                 lrow += ps2.x + ps2.y;
;                 bf16x8 pb[2]; pb[0] = pack8(sc, 0); pb[1] = pack8(sc, 1);
; #pragma unroll
;                 for (int i = 0; i < NPV; ++i) {
;                     VWAIT(2 * ((NPV - 1 - i) < (DV - 1) ? (NPV - 1 - i) : (DV - 1)), vlo[i % DV], vhi[i % DV]);
;                     const bf16x8 vf = __builtin_shufflevector(vlo[i % DV], vhi[i % DV], 0, 1, 2, 3, 4, 5, 6, 7);
;                     o[i >> 1] = mfma32(vf, pb[i & 1], o[i >> 1]);
;                     if (i + DV < NPV) LDV(i + DV, hf);
;                 }
.Lpc_skip2_i1:
	s_waitcnt lgkmcnt(5)
	v_mfma_f32_32x32x16_bf16 v[226:241], v[2:5], v[120:123], v[226:241]
	ds_read_b64_tr_b16 v[2:3], v173 offset:0
	ds_read_b64_tr_b16 v[4:5], v173 offset:2560
	v_add_f32_e32 v172, v172, v84
	v_add_f32_e32 v196, v196, v85
	v_cvt_pk_bf16_f32 v82, v84, v85
	v_exp_f32_e32 v86, v86
	v_exp_f32_e32 v87, v87
	s_waitcnt lgkmcnt(6)
	v_mfma_f32_32x32x16_bf16 v[226:241], v[6:9], v[124:127], v[226:241]
	ds_read_b64_tr_b16 v[6:7], v173 offset:64
	ds_read_b64_tr_b16 v[8:9], v173 offset:2624
	v_add_f32_e32 v172, v172, v86
	v_add_f32_e32 v196, v196, v87
	v_cvt_pk_bf16_f32 v83, v86, v87
	v_exp_f32_e32 v88, v88
	v_exp_f32_e32 v89, v89
	s_waitcnt lgkmcnt(7)
	v_mfma_f32_32x32x16_bf16 v[226:241], v[10:13], v[128:131], v[226:241]
	ds_read_b64_tr_b16 v[10:11], v173 offset:128
	ds_read_b64_tr_b16 v[12:13], v173 offset:2688
	v_add_f32_e32 v172, v172, v88
	v_add_f32_e32 v196, v196, v89
	v_cvt_pk_bf16_f32 v84, v88, v89
	v_exp_f32_e32 v90, v90
	v_exp_f32_e32 v91, v91
	s_waitcnt lgkmcnt(8)
	v_mfma_f32_32x32x16_bf16 v[226:241], v[174:177], v[132:135], v[226:241]
	ds_read_b64_tr_b16 v[174:175], v173 offset:192
	ds_read_b64_tr_b16 v[176:177], v173 offset:2752
	v_add_f32_e32 v172, v172, v90
	v_add_f32_e32 v196, v196, v91
	v_cvt_pk_bf16_f32 v85, v90, v91
	v_exp_f32_e32 v92, v92
	v_exp_f32_e32 v93, v93
	s_waitcnt lgkmcnt(9)
	v_mfma_f32_32x32x16_bf16 v[226:241], v[178:181], v[136:139], v[226:241]
	ds_read_b64_tr_b16 v[178:179], v173 offset:5120
	ds_read_b64_tr_b16 v[180:181], v173 offset:7680
	v_add_f32_e32 v172, v172, v92
	v_add_f32_e32 v196, v196, v93
	v_cvt_pk_bf16_f32 v86, v92, v93
	v_exp_f32_e32 v94, v94
	s_waitcnt lgkmcnt(10)
	v_mfma_f32_32x32x16_bf16 v[226:241], v[182:185], v[140:143], v[226:241]
	ds_read_b64_tr_b16 v[182:183], v173 offset:5184
	ds_read_b64_tr_b16 v[184:185], v173 offset:7744
	v_exp_f32_e32 v95, v95
	v_add_f32_e32 v172, v172, v94
	v_add_f32_e32 v196, v196, v95
	v_cvt_pk_bf16_f32 v87, v94, v95
	s_waitcnt lgkmcnt(10)
	v_mfma_f32_32x32x16_bf16 v[64:79], v[2:5], v[80:83], v[64:79]
	ds_read_b64_tr_b16 v[2:3], v173 offset:5248
	ds_read_b64_tr_b16 v[4:5], v173 offset:7808
	s_cmp_lg_u32 s99, 0
	s_cbranch_scc0 .Lpc_skip3_i1
	s_and_b64 vcc, exec, s[10:11]
	s_cbranch_vccnz .Lpc_skip3_i1
	v_lshl_add_u64 v[244:245], s[36:37], 0, v[152:153]
	v_lshl_add_u64 v[246:247], s[36:37], 0, v[164:165]
	v_cndmask_b32_e64 v245, v247, v245, s[20:21]
	v_cndmask_b32_e64 v244, v246, v244, s[20:21]
	s_add_i32 m0, s98, s82
	s_nop 0
	global_load_lds_dwordx4 v[244:245], off
.Lpc_skip3_i1:
	s_waitcnt lgkmcnt(10)
	v_mfma_f32_32x32x16_bf16 v[48:63], v[6:9], v[80:83], v[48:63]
	ds_read_b64_tr_b16 v[6:7], v173 offset:5312
	ds_read_b64_tr_b16 v[8:9], v173 offset:7872
	s_waitcnt lgkmcnt(10)
	v_mfma_f32_32x32x16_bf16 v[32:47], v[10:13], v[80:83], v[32:47]
	ds_read_b64_tr_b16 v[10:11], v173 offset:10240
	ds_read_b64_tr_b16 v[12:13], v173 offset:12800
	v_exp_f32_e32 v226, v226
	v_exp_f32_e32 v227, v227
	v_add_f32_e32 v172, v172, v226
	v_add_f32_e32 v196, v196, v227
	s_waitcnt lgkmcnt(10)
	v_mfma_f32_32x32x16_bf16 v[16:31], v[174:177], v[80:83], v[16:31]
	ds_read_b64_tr_b16 v[174:175], v173 offset:10304
	ds_read_b64_tr_b16 v[176:177], v173 offset:12864
	v_cvt_pk_bf16_f32 v226, v226, v227
	v_exp_f32_e32 v228, v228
	v_exp_f32_e32 v229, v229
	v_add_f32_e32 v172, v172, v228
	s_waitcnt lgkmcnt(10)
	v_mfma_f32_32x32x16_bf16 v[64:79], v[178:181], v[84:87], v[64:79]
	ds_read_b64_tr_b16 v[178:179], v173 offset:10368
	ds_read_b64_tr_b16 v[180:181], v173 offset:12928
	v_add_f32_e32 v196, v196, v229
	v_cvt_pk_bf16_f32 v227, v228, v229
	v_exp_f32_e32 v230, v230
	v_exp_f32_e32 v231, v231
	s_waitcnt lgkmcnt(10)
	v_mfma_f32_32x32x16_bf16 v[48:63], v[182:185], v[84:87], v[48:63]
	ds_read_b64_tr_b16 v[182:183], v173 offset:10432
	ds_read_b64_tr_b16 v[184:185], v173 offset:12992
	v_add_f32_e32 v172, v172, v230
	v_add_f32_e32 v196, v196, v231
	v_cvt_pk_bf16_f32 v228, v230, v231
	v_exp_f32_e32 v232, v232
	s_waitcnt lgkmcnt(10)
	v_mfma_f32_32x32x16_bf16 v[32:47], v[2:5], v[84:87], v[32:47]
	ds_read_b64_tr_b16 v[2:3], v173 offset:15360
	ds_read_b64_tr_b16 v[4:5], v173 offset:17920
	v_exp_f32_e32 v233, v233
	v_add_f32_e32 v172, v172, v232
	v_add_f32_e32 v196, v196, v233
	v_cvt_pk_bf16_f32 v229, v232, v233
	s_waitcnt lgkmcnt(10)
	v_mfma_f32_32x32x16_bf16 v[16:31], v[6:9], v[84:87], v[16:31]
	ds_read_b64_tr_b16 v[6:7], v173 offset:15424
	ds_read_b64_tr_b16 v[8:9], v173 offset:17984
	s_cmp_lg_u32 s99, 0
	s_cbranch_scc0 .Lpc_skip5_i1
	s_and_b64 vcc, exec, s[12:13]
	s_cbranch_vccnz .Lpc_skip5_i1
	v_lshl_add_u64 v[244:245], s[36:37], 0, v[154:155]
	v_lshl_add_u64 v[246:247], s[36:37], 0, v[166:167]
	v_cndmask_b32_e64 v245, v247, v245, s[22:23]
	v_cndmask_b32_e64 v244, v246, v244, s[22:23]
	s_add_i32 m0, s98, s83
	s_nop 0
	global_load_lds_dwordx4 v[244:245], off
.Lpc_skip5_i1:
	s_waitcnt lgkmcnt(10)
	v_mfma_f32_32x32x16_bf16 v[64:79], v[10:13], v[226:229], v[64:79]
	ds_read_b64_tr_b16 v[10:11], v173 offset:15488
	ds_read_b64_tr_b16 v[12:13], v173 offset:18048
	v_exp_f32_e32 v234, v234
	v_exp_f32_e32 v235, v235
	v_add_f32_e32 v172, v172, v234
	v_add_f32_e32 v196, v196, v235
	v_cvt_pk_bf16_f32 v230, v234, v235
	s_waitcnt lgkmcnt(10)
	v_mfma_f32_32x32x16_bf16 v[48:63], v[174:177], v[226:229], v[48:63]
	ds_read_b64_tr_b16 v[174:175], v173 offset:15552
	ds_read_b64_tr_b16 v[176:177], v173 offset:18112
	v_exp_f32_e32 v236, v236
	v_exp_f32_e32 v237, v237
	v_add_f32_e32 v172, v172, v236
	v_add_f32_e32 v196, v196, v237
	v_cvt_pk_bf16_f32 v231, v236, v237
	s_waitcnt lgkmcnt(10)
	v_mfma_f32_32x32x16_bf16 v[32:47], v[178:181], v[226:229], v[32:47]
	v_exp_f32_e32 v238, v238
	v_exp_f32_e32 v239, v239
	v_add_f32_e32 v172, v172, v238
	v_add_f32_e32 v196, v196, v239
	v_cvt_pk_bf16_f32 v232, v238, v239
	s_waitcnt lgkmcnt(8)
	v_mfma_f32_32x32x16_bf16 v[16:31], v[182:185], v[226:229], v[16:31]
	v_exp_f32_e32 v240, v240
	v_exp_f32_e32 v241, v241
	v_add_f32_e32 v172, v172, v240
	v_add_f32_e32 v196, v196, v241
	v_cvt_pk_bf16_f32 v233, v240, v241
	s_waitcnt lgkmcnt(6)
	s_nop 0
	v_mfma_f32_32x32x16_bf16 v[64:79], v[2:5], v[230:233], v[64:79]
	s_waitcnt lgkmcnt(4)
	v_mfma_f32_32x32x16_bf16 v[48:63], v[6:9], v[230:233], v[48:63]
	s_waitcnt lgkmcnt(2)
	v_mfma_f32_32x32x16_bf16 v[32:47], v[10:13], v[230:233], v[32:47]
	s_cmp_lg_u32 s99, 0
	s_cbranch_scc0 .Lpc_skip4_i1
	s_andn2_b64 vcc, exec, s[68:69]
	s_cbranch_vccnz .Lpc_skip4_i1
	v_lshl_add_u64 v[244:245], s[36:37], 0, v[156:157]
	v_lshl_add_u64 v[246:247], s[36:37], 0, v[168:169]
	v_cndmask_b32_e64 v245, v247, v245, s[24:25]
	v_cndmask_b32_e64 v244, v246, v244, s[24:25]
	s_add_i32 m0, s98, s46
	s_nop 0
	global_load_lds_dwordx4 v[244:245], off
.Lpc_skip4_i1:
	s_waitcnt lgkmcnt(0)
	v_mfma_f32_32x32x16_bf16 v[16:31], v[174:177], v[230:233], v[16:31]
	v_add_f32_e32 v172, v172, v196
	s_cmp_ge_u32 s84, s31
	s_mov_b64 s[80:81], -1
	s_cbranch_scc0 .LBB0_1388
